# P2b s5_sample: all per-item loads (state, B rows, lambda) issued at item top, one round trip instead of four
# speedup vs baseline: 1.0029x; 1.0029x over previous
.LBB0_538:
	v_ashrrev_i32_e32 v8, 5, v3
	v_ashrrev_i32_e32 v9, 31, v8
	v_and_b32_e32 v22, 31, v3
	s_waitcnt lgkmcnt(0)
	v_lshlrev_b64 v[12:13], 5, v[8:9]
	v_or_b32_e32 v12, v12, v22
	v_lshlrev_b64 v[10:11], 5, v[12:13]
	v_lshl_add_u64 v[10:11], s[24:25], 0, v[10:11]
	global_load_dwordx4 v[24:27], v[10:11], off offset:16
	global_load_dwordx4 v[28:31], v[10:11], off
	v_lshl_or_b32 v96, v22, 12, v21
	global_load_dword v64, v96, s[8:9]
	global_load_dword v80, v96, s[10:11]
	global_load_dword v65, v96, s[8:9] offset:256
	global_load_dword v81, v96, s[10:11] offset:256
	global_load_dword v66, v96, s[8:9] offset:512
	global_load_dword v82, v96, s[10:11] offset:512
	global_load_dword v67, v96, s[8:9] offset:768
	global_load_dword v83, v96, s[10:11] offset:768
	global_load_dword v68, v96, s[8:9] offset:1024
	global_load_dword v84, v96, s[10:11] offset:1024
	global_load_dword v69, v96, s[8:9] offset:1280
	global_load_dword v85, v96, s[10:11] offset:1280
	global_load_dword v70, v96, s[8:9] offset:1536
	global_load_dword v86, v96, s[10:11] offset:1536
	global_load_dword v71, v96, s[8:9] offset:1792
	global_load_dword v87, v96, s[10:11] offset:1792
	global_load_dword v72, v96, s[8:9] offset:2048
	global_load_dword v88, v96, s[10:11] offset:2048
	global_load_dword v73, v96, s[8:9] offset:2304
	global_load_dword v89, v96, s[10:11] offset:2304
	global_load_dword v74, v96, s[8:9] offset:2560
	global_load_dword v90, v96, s[10:11] offset:2560
	global_load_dword v75, v96, s[8:9] offset:2816
	global_load_dword v91, v96, s[10:11] offset:2816
	global_load_dword v76, v96, s[8:9] offset:3072
	global_load_dword v92, v96, s[10:11] offset:3072
	global_load_dword v77, v96, s[8:9] offset:3328
	global_load_dword v93, v96, s[10:11] offset:3328
	global_load_dword v78, v96, s[8:9] offset:3584
	global_load_dword v94, v96, s[10:11] offset:3584
	global_load_dword v79, v96, s[8:9] offset:3840
	global_load_dword v95, v96, s[10:11] offset:3840
	v_readlane_b32 s4, v250, 39
	v_readlane_b32 s5, v250, 40
	s_nop 1
	v_lshl_or_b32 v97, v22, 6, v2
	v_lshlrev_b32_e32 v98, 3, v97
	v_lshlrev_b32_e32 v99, 7, v97
	v_lshlrev_b64 v[136:137], 8, v[12:13]
	v_lshl_or_b32 v136, v2, 2, v136
	v_lshl_add_u64 v[138:139], s[76:77], 0, v[136:137]
	v_lshl_add_u64 v[140:141], s[78:79], 0, v[136:137]
	global_load_dwordx2 v[132:133], v98, s[4:5]
	global_load_dwordx4 v[100:103], v99, s[2:3] offset:48
	global_load_dwordx4 v[104:107], v99, s[2:3] offset:32
	global_load_dwordx4 v[108:111], v99, s[2:3] offset:16
	global_load_dwordx4 v[112:115], v99, s[2:3]
	global_load_dwordx4 v[116:119], v99, s[2:3] offset:112
	global_load_dwordx4 v[120:123], v99, s[2:3] offset:96
	global_load_dwordx4 v[124:127], v99, s[2:3] offset:80
	global_load_dwordx4 v[128:131], v99, s[2:3] offset:64
	global_load_dword v134, v[138:139], off
	global_load_dword v135, v[140:141], off
	s_waitcnt vmcnt(44)
	v_lshlrev_b32_e32 v48, 16, v24
	v_and_b32_e32 v49, 0xffff0000, v24
	v_lshl_or_b32 v24, v22, 6, v2
	v_lshlrev_b32_e32 v14, 3, v24
	v_lshlrev_b32_e32 v56, 7, v24
	s_waitcnt vmcnt(43)
	v_lshlrev_b32_e32 v4, 16, v28
	v_and_b32_e32 v23, 0xffff0000, v28
	v_lshlrev_b32_e32 v32, 16, v29
	v_and_b32_e32 v33, 0xffff0000, v29
	v_lshlrev_b32_e32 v44, 16, v30
	v_and_b32_e32 v45, 0xffff0000, v30
	v_lshlrev_b32_e32 v46, 16, v31
	v_and_b32_e32 v47, 0xffff0000, v31
	v_lshlrev_b32_e32 v50, 16, v25
	v_and_b32_e32 v51, 0xffff0000, v25
	v_lshlrev_b32_e32 v52, 16, v26
	v_and_b32_e32 v53, 0xffff0000, v26
	v_lshlrev_b32_e32 v54, 16, v27
	v_and_b32_e32 v55, 0xffff0000, v27
	s_mov_b32 s4, 0x42f0000
	s_waitcnt vmcnt(0)
	v_fma_f32 v57, v112, v4, 0
	v_fma_f32 v58, v113, v4, 0
	v_fmac_f32_e32 v57, v114, v23
	v_fmac_f32_e32 v58, v115, v23
	v_fmac_f32_e32 v57, v108, v32
	v_fmac_f32_e32 v58, v109, v32
	v_fmac_f32_e32 v57, v110, v33
	v_fmac_f32_e32 v58, v111, v33
	v_fmac_f32_e32 v57, v104, v44
	v_fmac_f32_e32 v58, v105, v44
	v_fmac_f32_e32 v57, v106, v45
	v_fmac_f32_e32 v58, v107, v45
	v_fmac_f32_e32 v57, v100, v46
	v_fmac_f32_e32 v58, v101, v46
	v_fmac_f32_e32 v57, v102, v47
	v_fmac_f32_e32 v58, v103, v47
	v_fmac_f32_e32 v57, v128, v48
	v_fmac_f32_e32 v58, v129, v48
	v_fmac_f32_e32 v57, v130, v49
	v_fmac_f32_e32 v58, v131, v49
	v_fmac_f32_e32 v57, v124, v50
	v_fmac_f32_e32 v58, v125, v50
	v_fmac_f32_e32 v57, v126, v51
	v_fmac_f32_e32 v58, v127, v51
	v_fmac_f32_e32 v57, v120, v52
	v_fmac_f32_e32 v58, v121, v52
	v_fmac_f32_e32 v57, v122, v53
	v_fmac_f32_e32 v58, v123, v53
	v_fmac_f32_e32 v57, v116, v54
	v_fmac_f32_e32 v58, v117, v54
	v_lshlrev_b64 v[24:25], 8, v[12:13]
	v_lshl_or_b32 v24, v2, 2, v24
	v_fmac_f32_e32 v57, v118, v55
	v_fmac_f32_e32 v58, v119, v55
	v_lshl_or_b32 v13, v22, 12, v21
	s_nop 0
	v_mul_f32_e32 v4, v133, v135
	v_mul_f32_e32 v12, v132, v135
	v_fma_f32 v4, v132, v134, -v4
	v_fmac_f32_e32 v12, v133, v134
	v_lshl_add_u64 v[14:15], s[90:91], 0, v[24:25]
	v_add_co_u32_e32 v24, vcc, s4, v14
	s_mov_b32 s4, 0x43f0000
	s_nop 0
	v_addc_co_u32_e32 v25, vcc, 0, v15, vcc
	v_add_co_u32_e32 v14, vcc, s4, v14
	v_add_f32_e32 v4, v57, v4
	v_add_f32_e32 v12, v58, v12
	v_addc_co_u32_e32 v15, vcc, 0, v15, vcc
	global_store_dword v[24:25], v4, off
	global_store_dword v[14:15], v12, off
	v_mul_f32_e32 v15, v12, v80
	v_fma_f32 v14, v4, v64, -v15
	v_mul_f32_e32 v23, v12, v81
	v_fma_f32 v15, v4, v65, -v23
	v_mul_f32_e32 v24, v12, v82
	v_fma_f32 v23, v4, v66, -v24
	v_mul_f32_e32 v25, v12, v83
	v_fma_f32 v24, v4, v67, -v25
	v_mul_f32_e32 v26, v12, v84
	v_fma_f32 v25, v4, v68, -v26
	v_mul_f32_e32 v27, v12, v85
	v_fma_f32 v26, v4, v69, -v27
	v_mul_f32_e32 v28, v12, v86
	v_fma_f32 v27, v4, v70, -v28
	v_mul_f32_e32 v29, v12, v87
	v_fma_f32 v28, v4, v71, -v29
	v_mul_f32_e32 v30, v12, v88
	v_fma_f32 v29, v4, v72, -v30
	v_mul_f32_e32 v31, v12, v89
	v_fma_f32 v30, v4, v73, -v31
	v_mul_f32_e32 v32, v12, v90
	v_fma_f32 v31, v4, v74, -v32
	v_mul_f32_e32 v33, v12, v91
	v_fma_f32 v32, v4, v75, -v33
	v_mul_f32_e32 v36, v12, v92
	v_fma_f32 v33, v4, v76, -v36
	v_mul_f32_e32 v37, v12, v93
	v_fma_f32 v36, v4, v77, -v37
	v_mul_f32_e32 v38, v12, v94
	v_fma_f32 v37, v4, v78, -v38
	v_mul_f32_e32 v12, v12, v95
	v_cndmask_b32_e64 v13, v14, v29, s[38:39]
	ds_bpermute_b32 v13, v7, v13
	v_fma_f32 v4, v4, v79, -v12
	v_cndmask_b32_e64 v12, v29, v14, s[38:39]
	v_cndmask_b32_e64 v14, v15, v30, s[38:39]
	ds_bpermute_b32 v14, v7, v14
	s_waitcnt lgkmcnt(1)
	v_add_f32_e32 v12, v12, v13
	v_cndmask_b32_e64 v13, v30, v15, s[38:39]
	v_cndmask_b32_e64 v15, v23, v31, s[38:39]
	ds_bpermute_b32 v15, v7, v15
	s_waitcnt lgkmcnt(1)
	v_add_f32_e32 v13, v13, v14
	v_cndmask_b32_e64 v14, v31, v23, s[38:39]
	v_cndmask_b32_e64 v23, v24, v32, s[38:39]
	ds_bpermute_b32 v23, v7, v23
	s_waitcnt lgkmcnt(1)
	v_add_f32_e32 v14, v14, v15
	v_cndmask_b32_e64 v15, v32, v24, s[38:39]
	v_cndmask_b32_e64 v24, v25, v33, s[38:39]
	ds_bpermute_b32 v24, v7, v24
	s_waitcnt lgkmcnt(1)
	v_add_f32_e32 v15, v15, v23
	v_cndmask_b32_e64 v23, v33, v25, s[38:39]
	v_cndmask_b32_e64 v25, v26, v36, s[38:39]
	ds_bpermute_b32 v25, v7, v25
	s_waitcnt lgkmcnt(1)
	v_add_f32_e32 v23, v23, v24
	v_cndmask_b32_e64 v24, v36, v26, s[38:39]
	v_cndmask_b32_e64 v26, v27, v37, s[38:39]
	ds_bpermute_b32 v26, v7, v26
	s_waitcnt lgkmcnt(1)
	v_add_f32_e32 v24, v24, v25
	v_cndmask_b32_e64 v25, v37, v27, s[38:39]
	s_waitcnt lgkmcnt(0)
	v_add_f32_e32 v25, v25, v26
	v_cndmask_b32_e64 v26, v4, v28, s[38:39]
	v_cndmask_b32_e64 v4, v28, v4, s[38:39]
	ds_bpermute_b32 v4, v7, v4
	s_waitcnt lgkmcnt(0)
	v_add_f32_e32 v4, v26, v4
	v_cndmask_b32_e64 v26, v23, v12, s[40:41]
	v_cndmask_b32_e64 v12, v12, v23, s[40:41]
	v_cndmask_b32_e64 v23, v24, v13, s[40:41]
	v_cndmask_b32_e64 v13, v13, v24, s[40:41]
	ds_bpermute_b32 v13, v16, v13
	ds_bpermute_b32 v12, v16, v12
	s_waitcnt lgkmcnt(1)
	v_add_f32_e32 v13, v23, v13
	v_cndmask_b32_e64 v23, v25, v14, s[40:41]
	v_cndmask_b32_e64 v14, v14, v25, s[40:41]
	ds_bpermute_b32 v14, v16, v14
	s_waitcnt lgkmcnt(1)
	v_add_f32_e32 v12, v26, v12
	s_waitcnt lgkmcnt(0)
	v_add_f32_e32 v14, v23, v14
	v_cndmask_b32_e64 v23, v4, v15, s[40:41]
	v_cndmask_b32_e64 v4, v15, v4, s[40:41]
	ds_bpermute_b32 v4, v16, v4
	v_cndmask_b32_e64 v15, v14, v12, s[42:43]
	v_cndmask_b32_e64 v12, v12, v14, s[42:43]
	ds_bpermute_b32 v12, v17, v12
	s_waitcnt lgkmcnt(1)
	v_add_f32_e32 v4, v23, v4
	v_cndmask_b32_e64 v14, v4, v13, s[42:43]
	v_cndmask_b32_e64 v4, v13, v4, s[42:43]
	ds_bpermute_b32 v4, v17, v4
	s_waitcnt lgkmcnt(1)
	v_add_f32_e32 v12, v15, v12
	s_waitcnt lgkmcnt(0)
	v_add_f32_e32 v4, v14, v4
	v_cndmask_b32_e64 v13, v4, v12, s[44:45]
	v_cndmask_b32_e64 v4, v12, v4, s[44:45]
	ds_bpermute_b32 v4, v18, v4
	s_waitcnt lgkmcnt(0)
	v_add_f32_e32 v4, v13, v4
	ds_bpermute_b32 v12, v19, v4
	s_waitcnt lgkmcnt(0)
	v_add_f32_e32 v12, v4, v12
	ds_bpermute_b32 v13, v20, v12
	s_and_saveexec_b64 s[28:29], s[46:47]
	s_cbranch_execz .LBB0_537
	v_lshlrev_b32_e32 v4, 1, v6
	v_lshl_add_u64 v[10:11], v[10:11], 0, v[4:5]
	global_load_ushort v11, v[10:11], off
	v_lshlrev_b32_e32 v10, 2, v6
	v_lshl_or_b32 v10, v22, 6, v10
	global_load_dword v14, v10, s[12:13]
	s_waitcnt lgkmcnt(0)
	v_add_f32_e32 v12, v12, v13
	v_lshlrev_b64 v[8:9], 10, v[8:9]
	v_lshlrev_b32_e32 v10, 5, v22
	v_lshl_add_u64 v[8:9], s[68:69], 0, v[8:9]
	s_waitcnt vmcnt(1)
	v_lshlrev_b32_e32 v11, 16, v11
	s_waitcnt vmcnt(0)
	v_fmac_f32_e32 v12, v14, v11
	v_mul_f32_e32 v11, 0x3d372713, v12
	v_mul_f32_e32 v11, v12, v11
	v_fma_f32 v11, v12, v11, v12
	v_mul_f32_e32 v11, 0x3fcc422a, v11
	v_mul_f32_e32 v11, 0xbfb8aa3b, v11
	v_exp_f32_e32 v13, v11
	v_mov_b32_e32 v11, v5
	v_lshl_add_u64 v[8:9], v[8:9], 0, v[10:11]
	v_lshl_add_u64 v[8:9], v[8:9], 0, v[4:5]
	v_add_f32_e32 v10, 1.0, v13
	v_rcp_f32_e32 v10, v10
	v_add_co_u32_e32 v8, vcc, 0x1020000, v8
	v_mul_f32_e32 v4, v12, v10
	s_nop 0
	v_addc_co_u32_e32 v9, vcc, 0, v9, vcc
	v_cvt_pk_bf16_f32 v4, v4, v5
	global_store_short v[8:9], v4, off
	s_branch .LBB0_537
